# hand-scheduled w_in epilogue in layer 1 (gelu chains 8-way interleaved, folded gelu constants, scalar FMAs, v_rsq) on top of previous
# speedup vs baseline: 1.0235x; 1.0067x over previous
.LBB0_200:
	v_lshl_add_u32 v190, v1, 2, s11
	ds_read_b32 v34, v190
	s_lshl_b32 s3, s96, 2
	s_add_i32 s11, s11, s3
	v_lshl_add_u32 v35, v174, 2, s11
	ds_read_b128 v[42:45], v35 offset:1024
	s_waitcnt lgkmcnt(0)
	v_fmamk_f32 v34, v34, 0x3a800000, v187
	v_rsq_f32_e32 v251, v34
	s_add_i32 s3, s10, -3
	s_cmp_gt_u32 s3, 1
	ds_read_b128 v[46:49], v35 offset:1040
	ds_read_b128 v[38:41], v35 offset:1536
	ds_read_b128 v[34:37], v35 offset:1552
	s_cselect_b64 s[84:85], -1, 0
	s_cmp_lt_u32 s3, 2
	s_mov_b64 s[8:9], -1
	v_mov_b32_e32 v166, v251
	v_pk_fma_f32 v[170:171], v[144:145], v[166:167], v[44:45] op_sel_hi:[1,0,1]
	v_pk_fma_f32 v[144:145], v[142:143], v[166:167], v[42:43] op_sel_hi:[1,0,1]
	s_waitcnt lgkmcnt(0)
	v_pk_fma_f32 v[168:169], v[140:141], v[166:167], v[48:49] op_sel_hi:[1,0,1]
	v_pk_fma_f32 v[140:141], v[138:139], v[166:167], v[46:47] op_sel_hi:[1,0,1]
	s_cbranch_scc1 .LBB0_202
	v_pk_mov_b32 v[172:173], v[170:171], v[140:141] op_sel:[1,0]
	s_mov_b64 s[8:9], 0

.LBB0_212:
	ds_read_b32 v130, v190 offset:64
	s_waitcnt lgkmcnt(0)
	v_fmamk_f32 v130, v130, 0x3a800000, v187
	v_rsq_f32_e32 v252, v130
	s_mov_b64 s[10:11], -1
	v_mov_b32_e32 v130, v252
	v_pk_fma_f32 v[132:133], v[128:129], v[130:131], v[44:45] op_sel_hi:[1,0,1]
	v_pk_fma_f32 v[126:127], v[126:127], v[130:131], v[42:43] op_sel_hi:[1,0,1]
	v_pk_fma_f32 v[128:129], v[124:125], v[130:131], v[48:49] op_sel_hi:[1,0,1]
	v_pk_fma_f32 v[122:123], v[122:123], v[130:131], v[46:47] op_sel_hi:[1,0,1]
	s_and_b64 vcc, exec, s[8:9]
	s_cbranch_vccnz .LBB0_214
	v_pk_mov_b32 v[134:135], v[132:133], v[122:123] op_sel:[1,0]
	s_mov_b64 s[10:11], 0

.LBB0_224:
	ds_read_b32 v114, v190 offset:128
	s_waitcnt lgkmcnt(0)
	v_fmamk_f32 v114, v114, 0x3a800000, v187
	v_rsq_f32_e32 v253, v114
	s_mov_b64 s[14:15], -1
	s_nop 0
	v_mov_b32_e32 v114, v253
	v_pk_fma_f32 v[116:117], v[112:113], v[114:115], v[44:45] op_sel_hi:[1,0,1]
	v_pk_fma_f32 v[110:111], v[110:111], v[114:115], v[42:43] op_sel_hi:[1,0,1]
	v_pk_fma_f32 v[112:113], v[108:109], v[114:115], v[48:49] op_sel_hi:[1,0,1]
	v_pk_fma_f32 v[106:107], v[106:107], v[114:115], v[46:47] op_sel_hi:[1,0,1]
	s_and_b64 vcc, exec, s[8:9]
	s_cbranch_vccnz .LBB0_226
	v_pk_mov_b32 v[118:119], v[116:117], v[106:107] op_sel:[1,0]
	s_mov_b64 s[14:15], 0

.LBB0_236:
	ds_read_b32 v98, v190 offset:192
	s_waitcnt lgkmcnt(0)
	v_fmamk_f32 v98, v98, 0x3a800000, v187
	v_rsq_f32_e32 v254, v98
	s_mov_b64 s[14:15], -1
	s_nop 0
	v_mov_b32_e32 v98, v254
	v_pk_fma_f32 v[100:101], v[96:97], v[98:99], v[44:45] op_sel_hi:[1,0,1]
	v_pk_fma_f32 v[94:95], v[94:95], v[98:99], v[42:43] op_sel_hi:[1,0,1]
	v_pk_fma_f32 v[96:97], v[92:93], v[98:99], v[48:49] op_sel_hi:[1,0,1]
	v_pk_fma_f32 v[90:91], v[90:91], v[98:99], v[46:47] op_sel_hi:[1,0,1]
	s_and_b64 vcc, exec, s[8:9]
	s_cbranch_vccnz .LBB0_238
	v_pk_mov_b32 v[102:103], v[100:101], v[90:91] op_sel:[1,0]
	s_mov_b64 s[14:15], 0

.LBB0_248:
	ds_read_b32 v82, v190 offset:512
	s_waitcnt lgkmcnt(0)
	v_fmamk_f32 v82, v82, 0x3a800000, v187
	v_rsq_f32_e32 v251, v82
	s_mov_b64 s[14:15], -1
	s_nop 0
	v_mov_b32_e32 v82, v251
	v_pk_fma_f32 v[84:85], v[80:81], v[82:83], v[44:45] op_sel_hi:[1,0,1]
	v_pk_fma_f32 v[78:79], v[78:79], v[82:83], v[42:43] op_sel_hi:[1,0,1]
	v_pk_fma_f32 v[80:81], v[76:77], v[82:83], v[48:49] op_sel_hi:[1,0,1]
	v_pk_fma_f32 v[74:75], v[74:75], v[82:83], v[46:47] op_sel_hi:[1,0,1]
	s_and_b64 vcc, exec, s[8:9]
	s_cbranch_vccnz .LBB0_250
	v_pk_mov_b32 v[86:87], v[84:85], v[74:75] op_sel:[1,0]
	s_mov_b64 s[14:15], 0

.LBB0_260:
	ds_read_b32 v66, v190 offset:576
	s_waitcnt lgkmcnt(0)
	v_fmamk_f32 v66, v66, 0x3a800000, v187
	v_rsq_f32_e32 v252, v66
	s_mov_b64 s[14:15], -1
	s_nop 0
	v_mov_b32_e32 v66, v252
	v_pk_fma_f32 v[68:69], v[64:65], v[66:67], v[44:45] op_sel_hi:[1,0,1]
	v_pk_fma_f32 v[62:63], v[62:63], v[66:67], v[42:43] op_sel_hi:[1,0,1]
	v_pk_fma_f32 v[64:65], v[60:61], v[66:67], v[48:49] op_sel_hi:[1,0,1]
	v_pk_fma_f32 v[58:59], v[58:59], v[66:67], v[46:47] op_sel_hi:[1,0,1]
	s_and_b64 vcc, exec, s[8:9]
	s_cbranch_vccnz .LBB0_262
	v_pk_mov_b32 v[70:71], v[68:69], v[58:59] op_sel:[1,0]
	s_mov_b64 s[14:15], 0

.LBB0_272:
	ds_read_b32 v50, v190 offset:640
	s_waitcnt lgkmcnt(0)
	v_fmamk_f32 v50, v50, 0x3a800000, v187
	v_rsq_f32_e32 v253, v50
	s_mov_b64 s[14:15], -1
	s_nop 0
	v_mov_b32_e32 v50, v253
	v_pk_fma_f32 v[52:53], v[32:33], v[50:51], v[44:45] op_sel_hi:[1,0,1]
	v_pk_fma_f32 v[30:31], v[30:31], v[50:51], v[42:43] op_sel_hi:[1,0,1]
	v_pk_fma_f32 v[32:33], v[28:29], v[50:51], v[48:49] op_sel_hi:[1,0,1]
	v_pk_fma_f32 v[26:27], v[26:27], v[50:51], v[46:47] op_sel_hi:[1,0,1]
	s_and_b64 vcc, exec, s[8:9]
	s_cbranch_vccnz .LBB0_274
	v_pk_mov_b32 v[54:55], v[52:53], v[26:27] op_sel:[1,0]
	s_mov_b64 s[14:15], 0

.LBB0_284:
	ds_read_b32 v18, v190 offset:704
	s_waitcnt lgkmcnt(0)
	v_fmamk_f32 v18, v18, 0x3a800000, v187
	v_rsq_f32_e32 v254, v18
	s_mov_b64 s[14:15], -1
	s_nop 0
	v_mov_b32_e32 v18, v254
	v_pk_fma_f32 v[20:21], v[16:17], v[18:19], v[44:45] op_sel_hi:[1,0,1]
	v_pk_fma_f32 v[14:15], v[14:15], v[18:19], v[42:43] op_sel_hi:[1,0,1]
	v_pk_fma_f32 v[16:17], v[12:13], v[18:19], v[48:49] op_sel_hi:[1,0,1]
	v_pk_fma_f32 v[10:11], v[10:11], v[18:19], v[46:47] op_sel_hi:[1,0,1]
	s_and_b64 vcc, exec, s[8:9]
	s_cbranch_vccnz .LBB0_286
	v_pk_mov_b32 v[22:23], v[20:21], v[10:11] op_sel:[1,0]
	s_mov_b64 s[14:15], 0

.LBB0_994:
	v_lshl_or_b32 v226, s10, 8, v183
	v_lshl_add_u32 v222, v1, 2, s9
	ds_read_b32 v214, v222
	ds_read_b32 v215, v222 offset:64
	ds_read_b32 v216, v222 offset:128
	ds_read_b32 v217, v222 offset:192
	ds_read_b32 v218, v222 offset:512
	ds_read_b32 v219, v222 offset:576
	ds_read_b32 v220, v222 offset:640
	ds_read_b32 v221, v222 offset:704
	s_lshl_b32 s0, s92, 2
	s_add_i32 s0, s9, s0
	v_lshl_add_u32 v223, v174, 2, s0
	s_lshl_b32 s23, s8, 8
	ds_read_b128 v[42:45], v223 offset:1024
	ds_read_b128 v[46:49], v223 offset:1040
	ds_read_b128 v[38:41], v223 offset:1536
	ds_read_b128 v[34:37], v223 offset:1552
	v_ashrrev_i32_e32 v227, 31, v226
	v_lshlrev_b64 v[226:227], 1, v[226:227]
	v_lshl_add_u64 v[226:227], s[52:53], 0, v[226:227]
	v_xor_b32_e32 v224, 16, v189
	v_xor_b32_e32 v225, 32, v189
	v_lshlrev_b32_e32 v224, 2, v224
	v_lshlrev_b32_e32 v225, 2, v225
	v_mov_b32_e32 v170, 0xbdd2d3e7
	s_waitcnt lgkmcnt(4)
	v_fmamk_f32 v214, v214, 0x3a800000, v187
	v_fmamk_f32 v215, v215, 0x3a800000, v187
	v_fmamk_f32 v216, v216, 0x3a800000, v187
	v_fmamk_f32 v217, v217, 0x3a800000, v187
	v_fmamk_f32 v218, v218, 0x3a800000, v187
	v_fmamk_f32 v219, v219, 0x3a800000, v187
	v_fmamk_f32 v220, v220, 0x3a800000, v187
	v_fmamk_f32 v221, v221, 0x3a800000, v187
	v_rsq_f32_e32 v214, v214
	v_rsq_f32_e32 v215, v215
	v_rsq_f32_e32 v216, v216
	v_rsq_f32_e32 v217, v217
	v_rsq_f32_e32 v218, v218
	v_rsq_f32_e32 v219, v219
	v_rsq_f32_e32 v220, v220
	v_rsq_f32_e32 v221, v221
	s_waitcnt lgkmcnt(0)
	s_add_i32 s0, s10, -3
	s_cmp_gt_u32 s0, 1
	s_cbranch_scc1 .Lwin_plain_l1
	v_fma_f32 v142, v142, v214, v42
	v_fma_f32 v143, v143, v214, v43
	v_fma_f32 v144, v144, v214, v44
	v_fma_f32 v145, v145, v214, v45
	v_fma_f32 v138, v138, v214, v46
	v_fma_f32 v139, v139, v214, v47
	v_fma_f32 v140, v140, v214, v48
	v_fma_f32 v141, v141, v214, v49
	v_mul_f32_e32 v190, v142, v142
	v_mul_f32_e32 v191, v143, v143
	v_mul_f32_e32 v192, v144, v144
	v_mul_f32_e32 v193, v145, v145
	v_mul_f32_e32 v194, v138, v138
	v_mul_f32_e32 v195, v139, v139
	v_mul_f32_e32 v196, v140, v140
	v_mul_f32_e32 v197, v141, v141
	v_fmaak_f32 v190, v190, v170, 0xc0135761
	v_fmaak_f32 v191, v191, v170, 0xc0135761
	v_fmaak_f32 v192, v192, v170, 0xc0135761
	v_fmaak_f32 v193, v193, v170, 0xc0135761
	v_fmaak_f32 v194, v194, v170, 0xc0135761
	v_fmaak_f32 v195, v195, v170, 0xc0135761
	v_fmaak_f32 v196, v196, v170, 0xc0135761
	v_fmaak_f32 v197, v197, v170, 0xc0135761
	v_add_u32_e32 v169, s23, v1
	v_mad_i64_i32 v[228:229], s[0:1], v169, s22, v[226:227]
	v_mul_f32_e32 v190, v190, v142
	v_mul_f32_e32 v191, v191, v143
	v_mul_f32_e32 v192, v192, v144
	v_mul_f32_e32 v193, v193, v145
	v_mul_f32_e32 v194, v194, v138
	v_mul_f32_e32 v195, v195, v139
	v_mul_f32_e32 v196, v196, v140
	v_mul_f32_e32 v197, v197, v141
	v_exp_f32_e32 v190, v190
	v_exp_f32_e32 v191, v191
	v_exp_f32_e32 v192, v192
	v_exp_f32_e32 v193, v193
	v_exp_f32_e32 v194, v194
	v_exp_f32_e32 v195, v195
	v_exp_f32_e32 v196, v196
	v_exp_f32_e32 v197, v197
	v_add_f32_e32 v190, 1.0, v190
	v_add_f32_e32 v191, 1.0, v191
	v_add_f32_e32 v192, 1.0, v192
	v_add_f32_e32 v193, 1.0, v193
	v_add_f32_e32 v194, 1.0, v194
	v_add_f32_e32 v195, 1.0, v195
	v_add_f32_e32 v196, 1.0, v196
	v_add_f32_e32 v197, 1.0, v197
	v_rcp_f32_e32 v190, v190
	v_rcp_f32_e32 v191, v191
	v_rcp_f32_e32 v192, v192
	v_rcp_f32_e32 v193, v193
	v_rcp_f32_e32 v194, v194
	v_rcp_f32_e32 v195, v195
	v_rcp_f32_e32 v196, v196
	v_rcp_f32_e32 v197, v197
	v_mul_f32_e32 v142, v142, v190
	v_mul_f32_e32 v143, v143, v191
	v_mul_f32_e32 v144, v144, v192
	v_mul_f32_e32 v145, v145, v193
	v_mul_f32_e32 v138, v138, v194
	v_mul_f32_e32 v139, v139, v195
	v_mul_f32_e32 v140, v140, v196
	v_mul_f32_e32 v141, v141, v197
	v_mul_f32_e32 v190, v142, v142
	v_mul_f32_e32 v191, v144, v144
	v_mul_f32_e32 v192, v138, v138
	v_mul_f32_e32 v193, v140, v140
	v_fmac_f32_e32 v190, v143, v143
	v_fmac_f32_e32 v191, v145, v145
	v_fmac_f32_e32 v192, v139, v139
	v_fmac_f32_e32 v193, v141, v141
	v_cvt_pk_bf16_f32 v198, v142, v143
	v_cvt_pk_bf16_f32 v199, v144, v145
	v_cvt_pk_bf16_f32 v200, v138, v139
	v_cvt_pk_bf16_f32 v201, v140, v141
	v_add_f32_e32 v190, v190, v191
	v_add_f32_e32 v192, v192, v193
	v_add_f32_e32 v190, v190, v192
	v_mov_b32_e32 v168, v190
	global_store_dwordx4 v[228:229], v[198:201], off
	v_fma_f32 v134, v134, v214, v38
	v_fma_f32 v135, v135, v214, v39
	v_fma_f32 v136, v136, v214, v40
	v_fma_f32 v137, v137, v214, v41
	v_fma_f32 v130, v130, v214, v34
	v_fma_f32 v131, v131, v214, v35
	v_fma_f32 v132, v132, v214, v36
	v_fma_f32 v133, v133, v214, v37
	v_mul_f32_e32 v190, v134, v134
	v_mul_f32_e32 v191, v135, v135
	v_mul_f32_e32 v192, v136, v136
	v_mul_f32_e32 v193, v137, v137
	v_mul_f32_e32 v194, v130, v130
	v_mul_f32_e32 v195, v131, v131
	v_mul_f32_e32 v196, v132, v132
	v_mul_f32_e32 v197, v133, v133
	v_fmaak_f32 v190, v190, v170, 0xc0135761
	v_fmaak_f32 v191, v191, v170, 0xc0135761
	v_fmaak_f32 v192, v192, v170, 0xc0135761
	v_fmaak_f32 v193, v193, v170, 0xc0135761
	v_fmaak_f32 v194, v194, v170, 0xc0135761
	v_fmaak_f32 v195, v195, v170, 0xc0135761
	v_fmaak_f32 v196, v196, v170, 0xc0135761
	v_fmaak_f32 v197, v197, v170, 0xc0135761
	v_mul_f32_e32 v190, v190, v134
	v_mul_f32_e32 v191, v191, v135
	v_mul_f32_e32 v192, v192, v136
	v_mul_f32_e32 v193, v193, v137
	v_mul_f32_e32 v194, v194, v130
	v_mul_f32_e32 v195, v195, v131
	v_mul_f32_e32 v196, v196, v132
	v_mul_f32_e32 v197, v197, v133
	v_exp_f32_e32 v190, v190
	v_exp_f32_e32 v191, v191
	v_exp_f32_e32 v192, v192
	v_exp_f32_e32 v193, v193
	v_exp_f32_e32 v194, v194
	v_exp_f32_e32 v195, v195
	v_exp_f32_e32 v196, v196
	v_exp_f32_e32 v197, v197
	v_add_f32_e32 v190, 1.0, v190
	v_add_f32_e32 v191, 1.0, v191
	v_add_f32_e32 v192, 1.0, v192
	v_add_f32_e32 v193, 1.0, v193
	v_add_f32_e32 v194, 1.0, v194
	v_add_f32_e32 v195, 1.0, v195
	v_add_f32_e32 v196, 1.0, v196
	v_add_f32_e32 v197, 1.0, v197
	v_rcp_f32_e32 v190, v190
	v_rcp_f32_e32 v191, v191
	v_rcp_f32_e32 v192, v192
	v_rcp_f32_e32 v193, v193
	v_rcp_f32_e32 v194, v194
	v_rcp_f32_e32 v195, v195
	v_rcp_f32_e32 v196, v196
	v_rcp_f32_e32 v197, v197
	v_mul_f32_e32 v134, v134, v190
	v_mul_f32_e32 v135, v135, v191
	v_mul_f32_e32 v136, v136, v192
	v_mul_f32_e32 v137, v137, v193
	v_mul_f32_e32 v130, v130, v194
	v_mul_f32_e32 v131, v131, v195
	v_mul_f32_e32 v132, v132, v196
	v_mul_f32_e32 v133, v133, v197
	v_mul_f32_e32 v190, v134, v134
	v_mul_f32_e32 v191, v136, v136
	v_mul_f32_e32 v192, v130, v130
	v_mul_f32_e32 v193, v132, v132
	v_fmac_f32_e32 v190, v135, v135
	v_fmac_f32_e32 v191, v137, v137
	v_fmac_f32_e32 v192, v131, v131
	v_fmac_f32_e32 v193, v133, v133
	v_cvt_pk_bf16_f32 v202, v134, v135
	v_cvt_pk_bf16_f32 v203, v136, v137
	v_cvt_pk_bf16_f32 v204, v130, v131
	v_cvt_pk_bf16_f32 v205, v132, v133
	v_add_f32_e32 v190, v190, v191
	v_add_f32_e32 v192, v192, v193
	v_add_f32_e32 v190, v190, v192
	v_add_f32_e32 v168, v168, v190
	global_store_dwordx4 v[228:229], v[202:205], off offset:256
	s_cmp_lg_u32 s10, 4
	s_cbranch_scc1 .Lwin_noat_l1_0
	ds_bpermute_b32 v171, v224, v168
	v_ashrrev_i32_e32 v173, 31, v169
	v_mov_b32_e32 v172, v169
	s_waitcnt lgkmcnt(0)
	v_add_f32_e32 v168, v168, v171
	ds_bpermute_b32 v171, v225, v168
	v_lshl_add_u64 v[172:173], v[172:173], 2, s[68:69]
	s_waitcnt lgkmcnt(0)
	v_add_f32_e32 v168, v168, v171
	s_mov_b64 s[84:85], exec
	s_and_b64 exec, exec, s[4:5]
	global_atomic_add_f32 v[172:173], v168, off
	s_mov_b64 exec, s[84:85]
.Lwin_noat_l1_0:
	v_fma_f32 v126, v126, v215, v42
	v_fma_f32 v127, v127, v215, v43
	v_fma_f32 v128, v128, v215, v44
	v_fma_f32 v129, v129, v215, v45
	v_fma_f32 v122, v122, v215, v46
	v_fma_f32 v123, v123, v215, v47
	v_fma_f32 v124, v124, v215, v48
	v_fma_f32 v125, v125, v215, v49
	v_mul_f32_e32 v190, v126, v126
	v_mul_f32_e32 v191, v127, v127
	v_mul_f32_e32 v192, v128, v128
	v_mul_f32_e32 v193, v129, v129
	v_mul_f32_e32 v194, v122, v122
	v_mul_f32_e32 v195, v123, v123
	v_mul_f32_e32 v196, v124, v124
	v_mul_f32_e32 v197, v125, v125
	v_fmaak_f32 v190, v190, v170, 0xc0135761
	v_fmaak_f32 v191, v191, v170, 0xc0135761
	v_fmaak_f32 v192, v192, v170, 0xc0135761
	v_fmaak_f32 v193, v193, v170, 0xc0135761
	v_fmaak_f32 v194, v194, v170, 0xc0135761
	v_fmaak_f32 v195, v195, v170, 0xc0135761
	v_fmaak_f32 v196, v196, v170, 0xc0135761
	v_fmaak_f32 v197, v197, v170, 0xc0135761
	v_add_u32_e32 v169, s23, v176
	v_mad_i64_i32 v[166:167], s[0:1], v169, s22, v[226:227]
	v_mul_f32_e32 v190, v190, v126
	v_mul_f32_e32 v191, v191, v127
	v_mul_f32_e32 v192, v192, v128
	v_mul_f32_e32 v193, v193, v129
	v_mul_f32_e32 v194, v194, v122
	v_mul_f32_e32 v195, v195, v123
	v_mul_f32_e32 v196, v196, v124
	v_mul_f32_e32 v197, v197, v125
	v_exp_f32_e32 v190, v190
	v_exp_f32_e32 v191, v191
	v_exp_f32_e32 v192, v192
	v_exp_f32_e32 v193, v193
	v_exp_f32_e32 v194, v194
	v_exp_f32_e32 v195, v195
	v_exp_f32_e32 v196, v196
	v_exp_f32_e32 v197, v197
	v_add_f32_e32 v190, 1.0, v190
	v_add_f32_e32 v191, 1.0, v191
	v_add_f32_e32 v192, 1.0, v192
	v_add_f32_e32 v193, 1.0, v193
	v_add_f32_e32 v194, 1.0, v194
	v_add_f32_e32 v195, 1.0, v195
	v_add_f32_e32 v196, 1.0, v196
	v_add_f32_e32 v197, 1.0, v197
	v_rcp_f32_e32 v190, v190
	v_rcp_f32_e32 v191, v191
	v_rcp_f32_e32 v192, v192
	v_rcp_f32_e32 v193, v193
	v_rcp_f32_e32 v194, v194
	v_rcp_f32_e32 v195, v195
	v_rcp_f32_e32 v196, v196
	v_rcp_f32_e32 v197, v197
	v_mul_f32_e32 v126, v126, v190
	v_mul_f32_e32 v127, v127, v191
	v_mul_f32_e32 v128, v128, v192
	v_mul_f32_e32 v129, v129, v193
	v_mul_f32_e32 v122, v122, v194
	v_mul_f32_e32 v123, v123, v195
	v_mul_f32_e32 v124, v124, v196
	v_mul_f32_e32 v125, v125, v197
	v_mul_f32_e32 v190, v126, v126
	v_mul_f32_e32 v191, v128, v128
	v_mul_f32_e32 v192, v122, v122
	v_mul_f32_e32 v193, v124, v124
	v_fmac_f32_e32 v190, v127, v127
	v_fmac_f32_e32 v191, v129, v129
	v_fmac_f32_e32 v192, v123, v123
	v_fmac_f32_e32 v193, v125, v125
	v_cvt_pk_bf16_f32 v206, v126, v127
	v_cvt_pk_bf16_f32 v207, v128, v129
	v_cvt_pk_bf16_f32 v208, v122, v123
	v_cvt_pk_bf16_f32 v209, v124, v125
	v_add_f32_e32 v190, v190, v191
	v_add_f32_e32 v192, v192, v193
	v_add_f32_e32 v190, v190, v192
	v_mov_b32_e32 v168, v190
	global_store_dwordx4 v[166:167], v[206:209], off
	v_fma_f32 v118, v118, v215, v38
	v_fma_f32 v119, v119, v215, v39
	v_fma_f32 v120, v120, v215, v40
	v_fma_f32 v121, v121, v215, v41
	v_fma_f32 v114, v114, v215, v34
	v_fma_f32 v115, v115, v215, v35
	v_fma_f32 v116, v116, v215, v36
	v_fma_f32 v117, v117, v215, v37
	v_mul_f32_e32 v190, v118, v118
	v_mul_f32_e32 v191, v119, v119
	v_mul_f32_e32 v192, v120, v120
	v_mul_f32_e32 v193, v121, v121
	v_mul_f32_e32 v194, v114, v114
	v_mul_f32_e32 v195, v115, v115
	v_mul_f32_e32 v196, v116, v116
	v_mul_f32_e32 v197, v117, v117
	v_fmaak_f32 v190, v190, v170, 0xc0135761
	v_fmaak_f32 v191, v191, v170, 0xc0135761
	v_fmaak_f32 v192, v192, v170, 0xc0135761
	v_fmaak_f32 v193, v193, v170, 0xc0135761
	v_fmaak_f32 v194, v194, v170, 0xc0135761
	v_fmaak_f32 v195, v195, v170, 0xc0135761
	v_fmaak_f32 v196, v196, v170, 0xc0135761
	v_fmaak_f32 v197, v197, v170, 0xc0135761
	v_mul_f32_e32 v190, v190, v118
	v_mul_f32_e32 v191, v191, v119
	v_mul_f32_e32 v192, v192, v120
	v_mul_f32_e32 v193, v193, v121
	v_mul_f32_e32 v194, v194, v114
	v_mul_f32_e32 v195, v195, v115
	v_mul_f32_e32 v196, v196, v116
	v_mul_f32_e32 v197, v197, v117
	v_exp_f32_e32 v190, v190
	v_exp_f32_e32 v191, v191
	v_exp_f32_e32 v192, v192
	v_exp_f32_e32 v193, v193
	v_exp_f32_e32 v194, v194
	v_exp_f32_e32 v195, v195
	v_exp_f32_e32 v196, v196
	v_exp_f32_e32 v197, v197
	v_add_f32_e32 v190, 1.0, v190
	v_add_f32_e32 v191, 1.0, v191
	v_add_f32_e32 v192, 1.0, v192
	v_add_f32_e32 v193, 1.0, v193
	v_add_f32_e32 v194, 1.0, v194
	v_add_f32_e32 v195, 1.0, v195
	v_add_f32_e32 v196, 1.0, v196
	v_add_f32_e32 v197, 1.0, v197
	v_rcp_f32_e32 v190, v190
	v_rcp_f32_e32 v191, v191
	v_rcp_f32_e32 v192, v192
	v_rcp_f32_e32 v193, v193
	v_rcp_f32_e32 v194, v194
	v_rcp_f32_e32 v195, v195
	v_rcp_f32_e32 v196, v196
	v_rcp_f32_e32 v197, v197
	v_mul_f32_e32 v118, v118, v190
	v_mul_f32_e32 v119, v119, v191
	v_mul_f32_e32 v120, v120, v192
	v_mul_f32_e32 v121, v121, v193
	v_mul_f32_e32 v114, v114, v194
	v_mul_f32_e32 v115, v115, v195
	v_mul_f32_e32 v116, v116, v196
	v_mul_f32_e32 v117, v117, v197
	v_mul_f32_e32 v190, v118, v118
	v_mul_f32_e32 v191, v120, v120
	v_mul_f32_e32 v192, v114, v114
	v_mul_f32_e32 v193, v116, v116
	v_fmac_f32_e32 v190, v119, v119
	v_fmac_f32_e32 v191, v121, v121
	v_fmac_f32_e32 v192, v115, v115
	v_fmac_f32_e32 v193, v117, v117
	v_cvt_pk_bf16_f32 v210, v118, v119
	v_cvt_pk_bf16_f32 v211, v120, v121
	v_cvt_pk_bf16_f32 v212, v114, v115
	v_cvt_pk_bf16_f32 v213, v116, v117
	v_add_f32_e32 v190, v190, v191
	v_add_f32_e32 v192, v192, v193
	v_add_f32_e32 v190, v190, v192
	v_add_f32_e32 v168, v168, v190
	global_store_dwordx4 v[166:167], v[210:213], off offset:256
	s_cmp_lg_u32 s10, 4
	s_cbranch_scc1 .Lwin_noat_l1_1
	ds_bpermute_b32 v171, v224, v168
	v_ashrrev_i32_e32 v173, 31, v169
	v_mov_b32_e32 v172, v169
	s_waitcnt lgkmcnt(0)
	v_add_f32_e32 v168, v168, v171
	ds_bpermute_b32 v171, v225, v168
	v_lshl_add_u64 v[172:173], v[172:173], 2, s[68:69]
	s_waitcnt lgkmcnt(0)
	v_add_f32_e32 v168, v168, v171
	s_mov_b64 s[84:85], exec
	s_and_b64 exec, exec, s[4:5]
	global_atomic_add_f32 v[172:173], v168, off
	s_mov_b64 exec, s[84:85]
.Lwin_noat_l1_1:
	v_fma_f32 v110, v110, v216, v42
	v_fma_f32 v111, v111, v216, v43
	v_fma_f32 v112, v112, v216, v44
	v_fma_f32 v113, v113, v216, v45
	v_fma_f32 v106, v106, v216, v46
	v_fma_f32 v107, v107, v216, v47
	v_fma_f32 v108, v108, v216, v48
	v_fma_f32 v109, v109, v216, v49
	v_mul_f32_e32 v190, v110, v110
	v_mul_f32_e32 v191, v111, v111
	v_mul_f32_e32 v192, v112, v112
	v_mul_f32_e32 v193, v113, v113
	v_mul_f32_e32 v194, v106, v106
	v_mul_f32_e32 v195, v107, v107
	v_mul_f32_e32 v196, v108, v108
	v_mul_f32_e32 v197, v109, v109
	v_fmaak_f32 v190, v190, v170, 0xc0135761
	v_fmaak_f32 v191, v191, v170, 0xc0135761
	v_fmaak_f32 v192, v192, v170, 0xc0135761
	v_fmaak_f32 v193, v193, v170, 0xc0135761
	v_fmaak_f32 v194, v194, v170, 0xc0135761
	v_fmaak_f32 v195, v195, v170, 0xc0135761
	v_fmaak_f32 v196, v196, v170, 0xc0135761
	v_fmaak_f32 v197, v197, v170, 0xc0135761
	v_add_u32_e32 v169, s23, v177
	v_mad_i64_i32 v[228:229], s[0:1], v169, s22, v[226:227]
	v_mul_f32_e32 v190, v190, v110
	v_mul_f32_e32 v191, v191, v111
	v_mul_f32_e32 v192, v192, v112
	v_mul_f32_e32 v193, v193, v113
	v_mul_f32_e32 v194, v194, v106
	v_mul_f32_e32 v195, v195, v107
	v_mul_f32_e32 v196, v196, v108
	v_mul_f32_e32 v197, v197, v109
	v_exp_f32_e32 v190, v190
	v_exp_f32_e32 v191, v191
	v_exp_f32_e32 v192, v192
	v_exp_f32_e32 v193, v193
	v_exp_f32_e32 v194, v194
	v_exp_f32_e32 v195, v195
	v_exp_f32_e32 v196, v196
	v_exp_f32_e32 v197, v197
	v_add_f32_e32 v190, 1.0, v190
	v_add_f32_e32 v191, 1.0, v191
	v_add_f32_e32 v192, 1.0, v192
	v_add_f32_e32 v193, 1.0, v193
	v_add_f32_e32 v194, 1.0, v194
	v_add_f32_e32 v195, 1.0, v195
	v_add_f32_e32 v196, 1.0, v196
	v_add_f32_e32 v197, 1.0, v197
	v_rcp_f32_e32 v190, v190
	v_rcp_f32_e32 v191, v191
	v_rcp_f32_e32 v192, v192
	v_rcp_f32_e32 v193, v193
	v_rcp_f32_e32 v194, v194
	v_rcp_f32_e32 v195, v195
	v_rcp_f32_e32 v196, v196
	v_rcp_f32_e32 v197, v197
	v_mul_f32_e32 v110, v110, v190
	v_mul_f32_e32 v111, v111, v191
	v_mul_f32_e32 v112, v112, v192
	v_mul_f32_e32 v113, v113, v193
	v_mul_f32_e32 v106, v106, v194
	v_mul_f32_e32 v107, v107, v195
	v_mul_f32_e32 v108, v108, v196
	v_mul_f32_e32 v109, v109, v197
	v_mul_f32_e32 v190, v110, v110
	v_mul_f32_e32 v191, v112, v112
	v_mul_f32_e32 v192, v106, v106
	v_mul_f32_e32 v193, v108, v108
	v_fmac_f32_e32 v190, v111, v111
	v_fmac_f32_e32 v191, v113, v113
	v_fmac_f32_e32 v192, v107, v107
	v_fmac_f32_e32 v193, v109, v109
	v_cvt_pk_bf16_f32 v198, v110, v111
	v_cvt_pk_bf16_f32 v199, v112, v113
	v_cvt_pk_bf16_f32 v200, v106, v107
	v_cvt_pk_bf16_f32 v201, v108, v109
	v_add_f32_e32 v190, v190, v191
	v_add_f32_e32 v192, v192, v193
	v_add_f32_e32 v190, v190, v192
	v_mov_b32_e32 v168, v190
	global_store_dwordx4 v[228:229], v[198:201], off
	v_fma_f32 v102, v102, v216, v38
	v_fma_f32 v103, v103, v216, v39
	v_fma_f32 v104, v104, v216, v40
	v_fma_f32 v105, v105, v216, v41
	v_fma_f32 v98, v98, v216, v34
	v_fma_f32 v99, v99, v216, v35
	v_fma_f32 v100, v100, v216, v36
	v_fma_f32 v101, v101, v216, v37
	v_mul_f32_e32 v190, v102, v102
	v_mul_f32_e32 v191, v103, v103
	v_mul_f32_e32 v192, v104, v104
	v_mul_f32_e32 v193, v105, v105
	v_mul_f32_e32 v194, v98, v98
	v_mul_f32_e32 v195, v99, v99
	v_mul_f32_e32 v196, v100, v100
	v_mul_f32_e32 v197, v101, v101
	v_fmaak_f32 v190, v190, v170, 0xc0135761
	v_fmaak_f32 v191, v191, v170, 0xc0135761
	v_fmaak_f32 v192, v192, v170, 0xc0135761
	v_fmaak_f32 v193, v193, v170, 0xc0135761
	v_fmaak_f32 v194, v194, v170, 0xc0135761
	v_fmaak_f32 v195, v195, v170, 0xc0135761
	v_fmaak_f32 v196, v196, v170, 0xc0135761
	v_fmaak_f32 v197, v197, v170, 0xc0135761
	v_mul_f32_e32 v190, v190, v102
	v_mul_f32_e32 v191, v191, v103
	v_mul_f32_e32 v192, v192, v104
	v_mul_f32_e32 v193, v193, v105
	v_mul_f32_e32 v194, v194, v98
	v_mul_f32_e32 v195, v195, v99
	v_mul_f32_e32 v196, v196, v100
	v_mul_f32_e32 v197, v197, v101
	v_exp_f32_e32 v190, v190
	v_exp_f32_e32 v191, v191
	v_exp_f32_e32 v192, v192
	v_exp_f32_e32 v193, v193
	v_exp_f32_e32 v194, v194
	v_exp_f32_e32 v195, v195
	v_exp_f32_e32 v196, v196
	v_exp_f32_e32 v197, v197
	v_add_f32_e32 v190, 1.0, v190
	v_add_f32_e32 v191, 1.0, v191
	v_add_f32_e32 v192, 1.0, v192
	v_add_f32_e32 v193, 1.0, v193
	v_add_f32_e32 v194, 1.0, v194
	v_add_f32_e32 v195, 1.0, v195
	v_add_f32_e32 v196, 1.0, v196
	v_add_f32_e32 v197, 1.0, v197
	v_rcp_f32_e32 v190, v190
	v_rcp_f32_e32 v191, v191
	v_rcp_f32_e32 v192, v192
	v_rcp_f32_e32 v193, v193
	v_rcp_f32_e32 v194, v194
	v_rcp_f32_e32 v195, v195
	v_rcp_f32_e32 v196, v196
	v_rcp_f32_e32 v197, v197
	v_mul_f32_e32 v102, v102, v190
	v_mul_f32_e32 v103, v103, v191
	v_mul_f32_e32 v104, v104, v192
	v_mul_f32_e32 v105, v105, v193
	v_mul_f32_e32 v98, v98, v194
	v_mul_f32_e32 v99, v99, v195
	v_mul_f32_e32 v100, v100, v196
	v_mul_f32_e32 v101, v101, v197
	v_mul_f32_e32 v190, v102, v102
	v_mul_f32_e32 v191, v104, v104
	v_mul_f32_e32 v192, v98, v98
	v_mul_f32_e32 v193, v100, v100
	v_fmac_f32_e32 v190, v103, v103
	v_fmac_f32_e32 v191, v105, v105
	v_fmac_f32_e32 v192, v99, v99
	v_fmac_f32_e32 v193, v101, v101
	v_cvt_pk_bf16_f32 v202, v102, v103
	v_cvt_pk_bf16_f32 v203, v104, v105
	v_cvt_pk_bf16_f32 v204, v98, v99
	v_cvt_pk_bf16_f32 v205, v100, v101
	v_add_f32_e32 v190, v190, v191
	v_add_f32_e32 v192, v192, v193
	v_add_f32_e32 v190, v190, v192
	v_add_f32_e32 v168, v168, v190
	global_store_dwordx4 v[228:229], v[202:205], off offset:256
	s_cmp_lg_u32 s10, 4
	s_cbranch_scc1 .Lwin_noat_l1_2
	ds_bpermute_b32 v171, v224, v168
	v_ashrrev_i32_e32 v173, 31, v169
	v_mov_b32_e32 v172, v169
	s_waitcnt lgkmcnt(0)
	v_add_f32_e32 v168, v168, v171
	ds_bpermute_b32 v171, v225, v168
	v_lshl_add_u64 v[172:173], v[172:173], 2, s[68:69]
	s_waitcnt lgkmcnt(0)
	v_add_f32_e32 v168, v168, v171
	s_mov_b64 s[84:85], exec
	s_and_b64 exec, exec, s[4:5]
	global_atomic_add_f32 v[172:173], v168, off
	s_mov_b64 exec, s[84:85]
.Lwin_noat_l1_2:
	v_fma_f32 v94, v94, v217, v42
	v_fma_f32 v95, v95, v217, v43
	v_fma_f32 v96, v96, v217, v44
	v_fma_f32 v97, v97, v217, v45
	v_fma_f32 v90, v90, v217, v46
	v_fma_f32 v91, v91, v217, v47
	v_fma_f32 v92, v92, v217, v48
	v_fma_f32 v93, v93, v217, v49
	v_mul_f32_e32 v190, v94, v94
	v_mul_f32_e32 v191, v95, v95
	v_mul_f32_e32 v192, v96, v96
	v_mul_f32_e32 v193, v97, v97
	v_mul_f32_e32 v194, v90, v90
	v_mul_f32_e32 v195, v91, v91
	v_mul_f32_e32 v196, v92, v92
	v_mul_f32_e32 v197, v93, v93
	v_fmaak_f32 v190, v190, v170, 0xc0135761
	v_fmaak_f32 v191, v191, v170, 0xc0135761
	v_fmaak_f32 v192, v192, v170, 0xc0135761
	v_fmaak_f32 v193, v193, v170, 0xc0135761
	v_fmaak_f32 v194, v194, v170, 0xc0135761
	v_fmaak_f32 v195, v195, v170, 0xc0135761
	v_fmaak_f32 v196, v196, v170, 0xc0135761
	v_fmaak_f32 v197, v197, v170, 0xc0135761
	v_add_u32_e32 v169, s23, v178
	v_mad_i64_i32 v[166:167], s[0:1], v169, s22, v[226:227]
	v_mul_f32_e32 v190, v190, v94
	v_mul_f32_e32 v191, v191, v95
	v_mul_f32_e32 v192, v192, v96
	v_mul_f32_e32 v193, v193, v97
	v_mul_f32_e32 v194, v194, v90
	v_mul_f32_e32 v195, v195, v91
	v_mul_f32_e32 v196, v196, v92
	v_mul_f32_e32 v197, v197, v93
	v_exp_f32_e32 v190, v190
	v_exp_f32_e32 v191, v191
	v_exp_f32_e32 v192, v192
	v_exp_f32_e32 v193, v193
	v_exp_f32_e32 v194, v194
	v_exp_f32_e32 v195, v195
	v_exp_f32_e32 v196, v196
	v_exp_f32_e32 v197, v197
	v_add_f32_e32 v190, 1.0, v190
	v_add_f32_e32 v191, 1.0, v191
	v_add_f32_e32 v192, 1.0, v192
	v_add_f32_e32 v193, 1.0, v193
	v_add_f32_e32 v194, 1.0, v194
	v_add_f32_e32 v195, 1.0, v195
	v_add_f32_e32 v196, 1.0, v196
	v_add_f32_e32 v197, 1.0, v197
	v_rcp_f32_e32 v190, v190
	v_rcp_f32_e32 v191, v191
	v_rcp_f32_e32 v192, v192
	v_rcp_f32_e32 v193, v193
	v_rcp_f32_e32 v194, v194
	v_rcp_f32_e32 v195, v195
	v_rcp_f32_e32 v196, v196
	v_rcp_f32_e32 v197, v197
	v_mul_f32_e32 v94, v94, v190
	v_mul_f32_e32 v95, v95, v191
	v_mul_f32_e32 v96, v96, v192
	v_mul_f32_e32 v97, v97, v193
	v_mul_f32_e32 v90, v90, v194
	v_mul_f32_e32 v91, v91, v195
	v_mul_f32_e32 v92, v92, v196
	v_mul_f32_e32 v93, v93, v197
	v_mul_f32_e32 v190, v94, v94
	v_mul_f32_e32 v191, v96, v96
	v_mul_f32_e32 v192, v90, v90
	v_mul_f32_e32 v193, v92, v92
	v_fmac_f32_e32 v190, v95, v95
	v_fmac_f32_e32 v191, v97, v97
	v_fmac_f32_e32 v192, v91, v91
	v_fmac_f32_e32 v193, v93, v93
	v_cvt_pk_bf16_f32 v206, v94, v95
	v_cvt_pk_bf16_f32 v207, v96, v97
	v_cvt_pk_bf16_f32 v208, v90, v91
	v_cvt_pk_bf16_f32 v209, v92, v93
	v_add_f32_e32 v190, v190, v191
	v_add_f32_e32 v192, v192, v193
	v_add_f32_e32 v190, v190, v192
	v_mov_b32_e32 v168, v190
	global_store_dwordx4 v[166:167], v[206:209], off
	v_fma_f32 v86, v86, v217, v38
	v_fma_f32 v87, v87, v217, v39
	v_fma_f32 v88, v88, v217, v40
	v_fma_f32 v89, v89, v217, v41
	v_fma_f32 v82, v82, v217, v34
	v_fma_f32 v83, v83, v217, v35
	v_fma_f32 v84, v84, v217, v36
	v_fma_f32 v85, v85, v217, v37
	v_mul_f32_e32 v190, v86, v86
	v_mul_f32_e32 v191, v87, v87
	v_mul_f32_e32 v192, v88, v88
	v_mul_f32_e32 v193, v89, v89
	v_mul_f32_e32 v194, v82, v82
	v_mul_f32_e32 v195, v83, v83
	v_mul_f32_e32 v196, v84, v84
	v_mul_f32_e32 v197, v85, v85
	v_fmaak_f32 v190, v190, v170, 0xc0135761
	v_fmaak_f32 v191, v191, v170, 0xc0135761
	v_fmaak_f32 v192, v192, v170, 0xc0135761
	v_fmaak_f32 v193, v193, v170, 0xc0135761
	v_fmaak_f32 v194, v194, v170, 0xc0135761
	v_fmaak_f32 v195, v195, v170, 0xc0135761
	v_fmaak_f32 v196, v196, v170, 0xc0135761
	v_fmaak_f32 v197, v197, v170, 0xc0135761
	v_mul_f32_e32 v190, v190, v86
	v_mul_f32_e32 v191, v191, v87
	v_mul_f32_e32 v192, v192, v88
	v_mul_f32_e32 v193, v193, v89
	v_mul_f32_e32 v194, v194, v82
	v_mul_f32_e32 v195, v195, v83
	v_mul_f32_e32 v196, v196, v84
	v_mul_f32_e32 v197, v197, v85
	v_exp_f32_e32 v190, v190
	v_exp_f32_e32 v191, v191
	v_exp_f32_e32 v192, v192
	v_exp_f32_e32 v193, v193
	v_exp_f32_e32 v194, v194
	v_exp_f32_e32 v195, v195
	v_exp_f32_e32 v196, v196
	v_exp_f32_e32 v197, v197
	v_add_f32_e32 v190, 1.0, v190
	v_add_f32_e32 v191, 1.0, v191
	v_add_f32_e32 v192, 1.0, v192
	v_add_f32_e32 v193, 1.0, v193
	v_add_f32_e32 v194, 1.0, v194
	v_add_f32_e32 v195, 1.0, v195
	v_add_f32_e32 v196, 1.0, v196
	v_add_f32_e32 v197, 1.0, v197
	v_rcp_f32_e32 v190, v190
	v_rcp_f32_e32 v191, v191
	v_rcp_f32_e32 v192, v192
	v_rcp_f32_e32 v193, v193
	v_rcp_f32_e32 v194, v194
	v_rcp_f32_e32 v195, v195
	v_rcp_f32_e32 v196, v196
	v_rcp_f32_e32 v197, v197
	v_mul_f32_e32 v86, v86, v190
	v_mul_f32_e32 v87, v87, v191
	v_mul_f32_e32 v88, v88, v192
	v_mul_f32_e32 v89, v89, v193
	v_mul_f32_e32 v82, v82, v194
	v_mul_f32_e32 v83, v83, v195
	v_mul_f32_e32 v84, v84, v196
	v_mul_f32_e32 v85, v85, v197
	v_mul_f32_e32 v190, v86, v86
	v_mul_f32_e32 v191, v88, v88
	v_mul_f32_e32 v192, v82, v82
	v_mul_f32_e32 v193, v84, v84
	v_fmac_f32_e32 v190, v87, v87
	v_fmac_f32_e32 v191, v89, v89
	v_fmac_f32_e32 v192, v83, v83
	v_fmac_f32_e32 v193, v85, v85
	v_cvt_pk_bf16_f32 v210, v86, v87
	v_cvt_pk_bf16_f32 v211, v88, v89
	v_cvt_pk_bf16_f32 v212, v82, v83
	v_cvt_pk_bf16_f32 v213, v84, v85
	v_add_f32_e32 v190, v190, v191
	v_add_f32_e32 v192, v192, v193
	v_add_f32_e32 v190, v190, v192
	v_add_f32_e32 v168, v168, v190
	global_store_dwordx4 v[166:167], v[210:213], off offset:256
	s_cmp_lg_u32 s10, 4
	s_cbranch_scc1 .Lwin_noat_l1_3
	ds_bpermute_b32 v171, v224, v168
	v_ashrrev_i32_e32 v173, 31, v169
	v_mov_b32_e32 v172, v169
	s_waitcnt lgkmcnt(0)
	v_add_f32_e32 v168, v168, v171
	ds_bpermute_b32 v171, v225, v168
	v_lshl_add_u64 v[172:173], v[172:173], 2, s[68:69]
	s_waitcnt lgkmcnt(0)
	v_add_f32_e32 v168, v168, v171
	s_mov_b64 s[84:85], exec
	s_and_b64 exec, exec, s[4:5]
	global_atomic_add_f32 v[172:173], v168, off
	s_mov_b64 exec, s[84:85]
.Lwin_noat_l1_3:
	v_fma_f32 v78, v78, v218, v42
	v_fma_f32 v79, v79, v218, v43
	v_fma_f32 v80, v80, v218, v44
	v_fma_f32 v81, v81, v218, v45
	v_fma_f32 v74, v74, v218, v46
	v_fma_f32 v75, v75, v218, v47
	v_fma_f32 v76, v76, v218, v48
	v_fma_f32 v77, v77, v218, v49
	v_mul_f32_e32 v190, v78, v78
	v_mul_f32_e32 v191, v79, v79
	v_mul_f32_e32 v192, v80, v80
	v_mul_f32_e32 v193, v81, v81
	v_mul_f32_e32 v194, v74, v74
	v_mul_f32_e32 v195, v75, v75
	v_mul_f32_e32 v196, v76, v76
	v_mul_f32_e32 v197, v77, v77
	v_fmaak_f32 v190, v190, v170, 0xc0135761
	v_fmaak_f32 v191, v191, v170, 0xc0135761
	v_fmaak_f32 v192, v192, v170, 0xc0135761
	v_fmaak_f32 v193, v193, v170, 0xc0135761
	v_fmaak_f32 v194, v194, v170, 0xc0135761
	v_fmaak_f32 v195, v195, v170, 0xc0135761
	v_fmaak_f32 v196, v196, v170, 0xc0135761
	v_fmaak_f32 v197, v197, v170, 0xc0135761
	v_add_u32_e32 v169, s23, v179
	v_mad_i64_i32 v[228:229], s[0:1], v169, s22, v[226:227]
	v_mul_f32_e32 v190, v190, v78
	v_mul_f32_e32 v191, v191, v79
	v_mul_f32_e32 v192, v192, v80
	v_mul_f32_e32 v193, v193, v81
	v_mul_f32_e32 v194, v194, v74
	v_mul_f32_e32 v195, v195, v75
	v_mul_f32_e32 v196, v196, v76
	v_mul_f32_e32 v197, v197, v77
	v_exp_f32_e32 v190, v190
	v_exp_f32_e32 v191, v191
	v_exp_f32_e32 v192, v192
	v_exp_f32_e32 v193, v193
	v_exp_f32_e32 v194, v194
	v_exp_f32_e32 v195, v195
	v_exp_f32_e32 v196, v196
	v_exp_f32_e32 v197, v197
	v_add_f32_e32 v190, 1.0, v190
	v_add_f32_e32 v191, 1.0, v191
	v_add_f32_e32 v192, 1.0, v192
	v_add_f32_e32 v193, 1.0, v193
	v_add_f32_e32 v194, 1.0, v194
	v_add_f32_e32 v195, 1.0, v195
	v_add_f32_e32 v196, 1.0, v196
	v_add_f32_e32 v197, 1.0, v197
	v_rcp_f32_e32 v190, v190
	v_rcp_f32_e32 v191, v191
	v_rcp_f32_e32 v192, v192
	v_rcp_f32_e32 v193, v193
	v_rcp_f32_e32 v194, v194
	v_rcp_f32_e32 v195, v195
	v_rcp_f32_e32 v196, v196
	v_rcp_f32_e32 v197, v197
	v_mul_f32_e32 v78, v78, v190
	v_mul_f32_e32 v79, v79, v191
	v_mul_f32_e32 v80, v80, v192
	v_mul_f32_e32 v81, v81, v193
	v_mul_f32_e32 v74, v74, v194
	v_mul_f32_e32 v75, v75, v195
	v_mul_f32_e32 v76, v76, v196
	v_mul_f32_e32 v77, v77, v197
	v_mul_f32_e32 v190, v78, v78
	v_mul_f32_e32 v191, v80, v80
	v_mul_f32_e32 v192, v74, v74
	v_mul_f32_e32 v193, v76, v76
	v_fmac_f32_e32 v190, v79, v79
	v_fmac_f32_e32 v191, v81, v81
	v_fmac_f32_e32 v192, v75, v75
	v_fmac_f32_e32 v193, v77, v77
	v_cvt_pk_bf16_f32 v198, v78, v79
	v_cvt_pk_bf16_f32 v199, v80, v81
	v_cvt_pk_bf16_f32 v200, v74, v75
	v_cvt_pk_bf16_f32 v201, v76, v77
	v_add_f32_e32 v190, v190, v191
	v_add_f32_e32 v192, v192, v193
	v_add_f32_e32 v190, v190, v192
	v_mov_b32_e32 v168, v190
	global_store_dwordx4 v[228:229], v[198:201], off
	v_fma_f32 v70, v70, v218, v38
	v_fma_f32 v71, v71, v218, v39
	v_fma_f32 v72, v72, v218, v40
	v_fma_f32 v73, v73, v218, v41
	v_fma_f32 v66, v66, v218, v34
	v_fma_f32 v67, v67, v218, v35
	v_fma_f32 v68, v68, v218, v36
	v_fma_f32 v69, v69, v218, v37
	v_mul_f32_e32 v190, v70, v70
	v_mul_f32_e32 v191, v71, v71
	v_mul_f32_e32 v192, v72, v72
	v_mul_f32_e32 v193, v73, v73
	v_mul_f32_e32 v194, v66, v66
	v_mul_f32_e32 v195, v67, v67
	v_mul_f32_e32 v196, v68, v68
	v_mul_f32_e32 v197, v69, v69
	v_fmaak_f32 v190, v190, v170, 0xc0135761
	v_fmaak_f32 v191, v191, v170, 0xc0135761
	v_fmaak_f32 v192, v192, v170, 0xc0135761
	v_fmaak_f32 v193, v193, v170, 0xc0135761
	v_fmaak_f32 v194, v194, v170, 0xc0135761
	v_fmaak_f32 v195, v195, v170, 0xc0135761
	v_fmaak_f32 v196, v196, v170, 0xc0135761
	v_fmaak_f32 v197, v197, v170, 0xc0135761
	v_mul_f32_e32 v190, v190, v70
	v_mul_f32_e32 v191, v191, v71
	v_mul_f32_e32 v192, v192, v72
	v_mul_f32_e32 v193, v193, v73
	v_mul_f32_e32 v194, v194, v66
	v_mul_f32_e32 v195, v195, v67
	v_mul_f32_e32 v196, v196, v68
	v_mul_f32_e32 v197, v197, v69
	v_exp_f32_e32 v190, v190
	v_exp_f32_e32 v191, v191
	v_exp_f32_e32 v192, v192
	v_exp_f32_e32 v193, v193
	v_exp_f32_e32 v194, v194
	v_exp_f32_e32 v195, v195
	v_exp_f32_e32 v196, v196
	v_exp_f32_e32 v197, v197
	v_add_f32_e32 v190, 1.0, v190
	v_add_f32_e32 v191, 1.0, v191
	v_add_f32_e32 v192, 1.0, v192
	v_add_f32_e32 v193, 1.0, v193
	v_add_f32_e32 v194, 1.0, v194
	v_add_f32_e32 v195, 1.0, v195
	v_add_f32_e32 v196, 1.0, v196
	v_add_f32_e32 v197, 1.0, v197
	v_rcp_f32_e32 v190, v190
	v_rcp_f32_e32 v191, v191
	v_rcp_f32_e32 v192, v192
	v_rcp_f32_e32 v193, v193
	v_rcp_f32_e32 v194, v194
	v_rcp_f32_e32 v195, v195
	v_rcp_f32_e32 v196, v196
	v_rcp_f32_e32 v197, v197
	v_mul_f32_e32 v70, v70, v190
	v_mul_f32_e32 v71, v71, v191
	v_mul_f32_e32 v72, v72, v192
	v_mul_f32_e32 v73, v73, v193
	v_mul_f32_e32 v66, v66, v194
	v_mul_f32_e32 v67, v67, v195
	v_mul_f32_e32 v68, v68, v196
	v_mul_f32_e32 v69, v69, v197
	v_mul_f32_e32 v190, v70, v70
	v_mul_f32_e32 v191, v72, v72
	v_mul_f32_e32 v192, v66, v66
	v_mul_f32_e32 v193, v68, v68
	v_fmac_f32_e32 v190, v71, v71
	v_fmac_f32_e32 v191, v73, v73
	v_fmac_f32_e32 v192, v67, v67
	v_fmac_f32_e32 v193, v69, v69
	v_cvt_pk_bf16_f32 v202, v70, v71
	v_cvt_pk_bf16_f32 v203, v72, v73
	v_cvt_pk_bf16_f32 v204, v66, v67
	v_cvt_pk_bf16_f32 v205, v68, v69
	v_add_f32_e32 v190, v190, v191
	v_add_f32_e32 v192, v192, v193
	v_add_f32_e32 v190, v190, v192
	v_add_f32_e32 v168, v168, v190
	global_store_dwordx4 v[228:229], v[202:205], off offset:256
	s_cmp_lg_u32 s10, 4
	s_cbranch_scc1 .Lwin_noat_l1_4
	ds_bpermute_b32 v171, v224, v168
	v_ashrrev_i32_e32 v173, 31, v169
	v_mov_b32_e32 v172, v169
	s_waitcnt lgkmcnt(0)
	v_add_f32_e32 v168, v168, v171
	ds_bpermute_b32 v171, v225, v168
	v_lshl_add_u64 v[172:173], v[172:173], 2, s[68:69]
	s_waitcnt lgkmcnt(0)
	v_add_f32_e32 v168, v168, v171
	s_mov_b64 s[84:85], exec
	s_and_b64 exec, exec, s[4:5]
	global_atomic_add_f32 v[172:173], v168, off
	s_mov_b64 exec, s[84:85]
.Lwin_noat_l1_4:
	v_fma_f32 v62, v62, v219, v42
	v_fma_f32 v63, v63, v219, v43
	v_fma_f32 v64, v64, v219, v44
	v_fma_f32 v65, v65, v219, v45
	v_fma_f32 v58, v58, v219, v46
	v_fma_f32 v59, v59, v219, v47
	v_fma_f32 v60, v60, v219, v48
	v_fma_f32 v61, v61, v219, v49
	v_mul_f32_e32 v190, v62, v62
	v_mul_f32_e32 v191, v63, v63
	v_mul_f32_e32 v192, v64, v64
	v_mul_f32_e32 v193, v65, v65
	v_mul_f32_e32 v194, v58, v58
	v_mul_f32_e32 v195, v59, v59
	v_mul_f32_e32 v196, v60, v60
	v_mul_f32_e32 v197, v61, v61
	v_fmaak_f32 v190, v190, v170, 0xc0135761
	v_fmaak_f32 v191, v191, v170, 0xc0135761
	v_fmaak_f32 v192, v192, v170, 0xc0135761
	v_fmaak_f32 v193, v193, v170, 0xc0135761
	v_fmaak_f32 v194, v194, v170, 0xc0135761
	v_fmaak_f32 v195, v195, v170, 0xc0135761
	v_fmaak_f32 v196, v196, v170, 0xc0135761
	v_fmaak_f32 v197, v197, v170, 0xc0135761
	v_add_u32_e32 v169, s23, v180
	v_mad_i64_i32 v[166:167], s[0:1], v169, s22, v[226:227]
	v_mul_f32_e32 v190, v190, v62
	v_mul_f32_e32 v191, v191, v63
	v_mul_f32_e32 v192, v192, v64
	v_mul_f32_e32 v193, v193, v65
	v_mul_f32_e32 v194, v194, v58
	v_mul_f32_e32 v195, v195, v59
	v_mul_f32_e32 v196, v196, v60
	v_mul_f32_e32 v197, v197, v61
	v_exp_f32_e32 v190, v190
	v_exp_f32_e32 v191, v191
	v_exp_f32_e32 v192, v192
	v_exp_f32_e32 v193, v193
	v_exp_f32_e32 v194, v194
	v_exp_f32_e32 v195, v195
	v_exp_f32_e32 v196, v196
	v_exp_f32_e32 v197, v197
	v_add_f32_e32 v190, 1.0, v190
	v_add_f32_e32 v191, 1.0, v191
	v_add_f32_e32 v192, 1.0, v192
	v_add_f32_e32 v193, 1.0, v193
	v_add_f32_e32 v194, 1.0, v194
	v_add_f32_e32 v195, 1.0, v195
	v_add_f32_e32 v196, 1.0, v196
	v_add_f32_e32 v197, 1.0, v197
	v_rcp_f32_e32 v190, v190
	v_rcp_f32_e32 v191, v191
	v_rcp_f32_e32 v192, v192
	v_rcp_f32_e32 v193, v193
	v_rcp_f32_e32 v194, v194
	v_rcp_f32_e32 v195, v195
	v_rcp_f32_e32 v196, v196
	v_rcp_f32_e32 v197, v197
	v_mul_f32_e32 v62, v62, v190
	v_mul_f32_e32 v63, v63, v191
	v_mul_f32_e32 v64, v64, v192
	v_mul_f32_e32 v65, v65, v193
	v_mul_f32_e32 v58, v58, v194
	v_mul_f32_e32 v59, v59, v195
	v_mul_f32_e32 v60, v60, v196
	v_mul_f32_e32 v61, v61, v197
	v_mul_f32_e32 v190, v62, v62
	v_mul_f32_e32 v191, v64, v64
	v_mul_f32_e32 v192, v58, v58
	v_mul_f32_e32 v193, v60, v60
	v_fmac_f32_e32 v190, v63, v63
	v_fmac_f32_e32 v191, v65, v65
	v_fmac_f32_e32 v192, v59, v59
	v_fmac_f32_e32 v193, v61, v61
	v_cvt_pk_bf16_f32 v206, v62, v63
	v_cvt_pk_bf16_f32 v207, v64, v65
	v_cvt_pk_bf16_f32 v208, v58, v59
	v_cvt_pk_bf16_f32 v209, v60, v61
	v_add_f32_e32 v190, v190, v191
	v_add_f32_e32 v192, v192, v193
	v_add_f32_e32 v190, v190, v192
	v_mov_b32_e32 v168, v190
	global_store_dwordx4 v[166:167], v[206:209], off
	v_fma_f32 v54, v54, v219, v38
	v_fma_f32 v55, v55, v219, v39
	v_fma_f32 v56, v56, v219, v40
	v_fma_f32 v57, v57, v219, v41
	v_fma_f32 v50, v50, v219, v34
	v_fma_f32 v51, v51, v219, v35
	v_fma_f32 v52, v52, v219, v36
	v_fma_f32 v53, v53, v219, v37
	v_mul_f32_e32 v190, v54, v54
	v_mul_f32_e32 v191, v55, v55
	v_mul_f32_e32 v192, v56, v56
	v_mul_f32_e32 v193, v57, v57
	v_mul_f32_e32 v194, v50, v50
	v_mul_f32_e32 v195, v51, v51
	v_mul_f32_e32 v196, v52, v52
	v_mul_f32_e32 v197, v53, v53
	v_fmaak_f32 v190, v190, v170, 0xc0135761
	v_fmaak_f32 v191, v191, v170, 0xc0135761
	v_fmaak_f32 v192, v192, v170, 0xc0135761
	v_fmaak_f32 v193, v193, v170, 0xc0135761
	v_fmaak_f32 v194, v194, v170, 0xc0135761
	v_fmaak_f32 v195, v195, v170, 0xc0135761
	v_fmaak_f32 v196, v196, v170, 0xc0135761
	v_fmaak_f32 v197, v197, v170, 0xc0135761
	v_mul_f32_e32 v190, v190, v54
	v_mul_f32_e32 v191, v191, v55
	v_mul_f32_e32 v192, v192, v56
	v_mul_f32_e32 v193, v193, v57
	v_mul_f32_e32 v194, v194, v50
	v_mul_f32_e32 v195, v195, v51
	v_mul_f32_e32 v196, v196, v52
	v_mul_f32_e32 v197, v197, v53
	v_exp_f32_e32 v190, v190
	v_exp_f32_e32 v191, v191
	v_exp_f32_e32 v192, v192
	v_exp_f32_e32 v193, v193
	v_exp_f32_e32 v194, v194
	v_exp_f32_e32 v195, v195
	v_exp_f32_e32 v196, v196
	v_exp_f32_e32 v197, v197
	v_add_f32_e32 v190, 1.0, v190
	v_add_f32_e32 v191, 1.0, v191
	v_add_f32_e32 v192, 1.0, v192
	v_add_f32_e32 v193, 1.0, v193
	v_add_f32_e32 v194, 1.0, v194
	v_add_f32_e32 v195, 1.0, v195
	v_add_f32_e32 v196, 1.0, v196
	v_add_f32_e32 v197, 1.0, v197
	v_rcp_f32_e32 v190, v190
	v_rcp_f32_e32 v191, v191
	v_rcp_f32_e32 v192, v192
	v_rcp_f32_e32 v193, v193
	v_rcp_f32_e32 v194, v194
	v_rcp_f32_e32 v195, v195
	v_rcp_f32_e32 v196, v196
	v_rcp_f32_e32 v197, v197
	v_mul_f32_e32 v54, v54, v190
	v_mul_f32_e32 v55, v55, v191
	v_mul_f32_e32 v56, v56, v192
	v_mul_f32_e32 v57, v57, v193
	v_mul_f32_e32 v50, v50, v194
	v_mul_f32_e32 v51, v51, v195
	v_mul_f32_e32 v52, v52, v196
	v_mul_f32_e32 v53, v53, v197
	v_mul_f32_e32 v190, v54, v54
	v_mul_f32_e32 v191, v56, v56
	v_mul_f32_e32 v192, v50, v50
	v_mul_f32_e32 v193, v52, v52
	v_fmac_f32_e32 v190, v55, v55
	v_fmac_f32_e32 v191, v57, v57
	v_fmac_f32_e32 v192, v51, v51
	v_fmac_f32_e32 v193, v53, v53
	v_cvt_pk_bf16_f32 v210, v54, v55
	v_cvt_pk_bf16_f32 v211, v56, v57
	v_cvt_pk_bf16_f32 v212, v50, v51
	v_cvt_pk_bf16_f32 v213, v52, v53
	v_add_f32_e32 v190, v190, v191
	v_add_f32_e32 v192, v192, v193
	v_add_f32_e32 v190, v190, v192
	v_add_f32_e32 v168, v168, v190
	global_store_dwordx4 v[166:167], v[210:213], off offset:256
	s_cmp_lg_u32 s10, 4
	s_cbranch_scc1 .Lwin_noat_l1_5
	ds_bpermute_b32 v171, v224, v168
	v_ashrrev_i32_e32 v173, 31, v169
	v_mov_b32_e32 v172, v169
	s_waitcnt lgkmcnt(0)
	v_add_f32_e32 v168, v168, v171
	ds_bpermute_b32 v171, v225, v168
	v_lshl_add_u64 v[172:173], v[172:173], 2, s[68:69]
	s_waitcnt lgkmcnt(0)
	v_add_f32_e32 v168, v168, v171
	s_mov_b64 s[84:85], exec
	s_and_b64 exec, exec, s[4:5]
	global_atomic_add_f32 v[172:173], v168, off
	s_mov_b64 exec, s[84:85]
.Lwin_noat_l1_5:
	v_fma_f32 v30, v30, v220, v42
	v_fma_f32 v31, v31, v220, v43
	v_fma_f32 v32, v32, v220, v44
	v_fma_f32 v33, v33, v220, v45
	v_fma_f32 v26, v26, v220, v46
	v_fma_f32 v27, v27, v220, v47
	v_fma_f32 v28, v28, v220, v48
	v_fma_f32 v29, v29, v220, v49
	v_mul_f32_e32 v190, v30, v30
	v_mul_f32_e32 v191, v31, v31
	v_mul_f32_e32 v192, v32, v32
	v_mul_f32_e32 v193, v33, v33
	v_mul_f32_e32 v194, v26, v26
	v_mul_f32_e32 v195, v27, v27
	v_mul_f32_e32 v196, v28, v28
	v_mul_f32_e32 v197, v29, v29
	v_fmaak_f32 v190, v190, v170, 0xc0135761
	v_fmaak_f32 v191, v191, v170, 0xc0135761
	v_fmaak_f32 v192, v192, v170, 0xc0135761
	v_fmaak_f32 v193, v193, v170, 0xc0135761
	v_fmaak_f32 v194, v194, v170, 0xc0135761
	v_fmaak_f32 v195, v195, v170, 0xc0135761
	v_fmaak_f32 v196, v196, v170, 0xc0135761
	v_fmaak_f32 v197, v197, v170, 0xc0135761
	v_add_u32_e32 v169, s23, v181
	v_mad_i64_i32 v[228:229], s[0:1], v169, s22, v[226:227]
	v_mul_f32_e32 v190, v190, v30
	v_mul_f32_e32 v191, v191, v31
	v_mul_f32_e32 v192, v192, v32
	v_mul_f32_e32 v193, v193, v33
	v_mul_f32_e32 v194, v194, v26
	v_mul_f32_e32 v195, v195, v27
	v_mul_f32_e32 v196, v196, v28
	v_mul_f32_e32 v197, v197, v29
	v_exp_f32_e32 v190, v190
	v_exp_f32_e32 v191, v191
	v_exp_f32_e32 v192, v192
	v_exp_f32_e32 v193, v193
	v_exp_f32_e32 v194, v194
	v_exp_f32_e32 v195, v195
	v_exp_f32_e32 v196, v196
	v_exp_f32_e32 v197, v197
	v_add_f32_e32 v190, 1.0, v190
	v_add_f32_e32 v191, 1.0, v191
	v_add_f32_e32 v192, 1.0, v192
	v_add_f32_e32 v193, 1.0, v193
	v_add_f32_e32 v194, 1.0, v194
	v_add_f32_e32 v195, 1.0, v195
	v_add_f32_e32 v196, 1.0, v196
	v_add_f32_e32 v197, 1.0, v197
	v_rcp_f32_e32 v190, v190
	v_rcp_f32_e32 v191, v191
	v_rcp_f32_e32 v192, v192
	v_rcp_f32_e32 v193, v193
	v_rcp_f32_e32 v194, v194
	v_rcp_f32_e32 v195, v195
	v_rcp_f32_e32 v196, v196
	v_rcp_f32_e32 v197, v197
	v_mul_f32_e32 v30, v30, v190
	v_mul_f32_e32 v31, v31, v191
	v_mul_f32_e32 v32, v32, v192
	v_mul_f32_e32 v33, v33, v193
	v_mul_f32_e32 v26, v26, v194
	v_mul_f32_e32 v27, v27, v195
	v_mul_f32_e32 v28, v28, v196
	v_mul_f32_e32 v29, v29, v197
	v_mul_f32_e32 v190, v30, v30
	v_mul_f32_e32 v191, v32, v32
	v_mul_f32_e32 v192, v26, v26
	v_mul_f32_e32 v193, v28, v28
	v_fmac_f32_e32 v190, v31, v31
	v_fmac_f32_e32 v191, v33, v33
	v_fmac_f32_e32 v192, v27, v27
	v_fmac_f32_e32 v193, v29, v29
	v_cvt_pk_bf16_f32 v198, v30, v31
	v_cvt_pk_bf16_f32 v199, v32, v33
	v_cvt_pk_bf16_f32 v200, v26, v27
	v_cvt_pk_bf16_f32 v201, v28, v29
	v_add_f32_e32 v190, v190, v191
	v_add_f32_e32 v192, v192, v193
	v_add_f32_e32 v190, v190, v192
	v_mov_b32_e32 v168, v190
	global_store_dwordx4 v[228:229], v[198:201], off
	v_fma_f32 v22, v22, v220, v38
	v_fma_f32 v23, v23, v220, v39
	v_fma_f32 v24, v24, v220, v40
	v_fma_f32 v25, v25, v220, v41
	v_fma_f32 v18, v18, v220, v34
	v_fma_f32 v19, v19, v220, v35
	v_fma_f32 v20, v20, v220, v36
	v_fma_f32 v21, v21, v220, v37
	v_mul_f32_e32 v190, v22, v22
	v_mul_f32_e32 v191, v23, v23
	v_mul_f32_e32 v192, v24, v24
	v_mul_f32_e32 v193, v25, v25
	v_mul_f32_e32 v194, v18, v18
	v_mul_f32_e32 v195, v19, v19
	v_mul_f32_e32 v196, v20, v20
	v_mul_f32_e32 v197, v21, v21
	v_fmaak_f32 v190, v190, v170, 0xc0135761
	v_fmaak_f32 v191, v191, v170, 0xc0135761
	v_fmaak_f32 v192, v192, v170, 0xc0135761
	v_fmaak_f32 v193, v193, v170, 0xc0135761
	v_fmaak_f32 v194, v194, v170, 0xc0135761
	v_fmaak_f32 v195, v195, v170, 0xc0135761
	v_fmaak_f32 v196, v196, v170, 0xc0135761
	v_fmaak_f32 v197, v197, v170, 0xc0135761
	v_mul_f32_e32 v190, v190, v22
	v_mul_f32_e32 v191, v191, v23
	v_mul_f32_e32 v192, v192, v24
	v_mul_f32_e32 v193, v193, v25
	v_mul_f32_e32 v194, v194, v18
	v_mul_f32_e32 v195, v195, v19
	v_mul_f32_e32 v196, v196, v20
	v_mul_f32_e32 v197, v197, v21
	v_exp_f32_e32 v190, v190
	v_exp_f32_e32 v191, v191
	v_exp_f32_e32 v192, v192
	v_exp_f32_e32 v193, v193
	v_exp_f32_e32 v194, v194
	v_exp_f32_e32 v195, v195
	v_exp_f32_e32 v196, v196
	v_exp_f32_e32 v197, v197
	v_add_f32_e32 v190, 1.0, v190
	v_add_f32_e32 v191, 1.0, v191
	v_add_f32_e32 v192, 1.0, v192
	v_add_f32_e32 v193, 1.0, v193
	v_add_f32_e32 v194, 1.0, v194
	v_add_f32_e32 v195, 1.0, v195
	v_add_f32_e32 v196, 1.0, v196
	v_add_f32_e32 v197, 1.0, v197
	v_rcp_f32_e32 v190, v190
	v_rcp_f32_e32 v191, v191
	v_rcp_f32_e32 v192, v192
	v_rcp_f32_e32 v193, v193
	v_rcp_f32_e32 v194, v194
	v_rcp_f32_e32 v195, v195
	v_rcp_f32_e32 v196, v196
	v_rcp_f32_e32 v197, v197
	v_mul_f32_e32 v22, v22, v190
	v_mul_f32_e32 v23, v23, v191
	v_mul_f32_e32 v24, v24, v192
	v_mul_f32_e32 v25, v25, v193
	v_mul_f32_e32 v18, v18, v194
	v_mul_f32_e32 v19, v19, v195
	v_mul_f32_e32 v20, v20, v196
	v_mul_f32_e32 v21, v21, v197
	v_mul_f32_e32 v190, v22, v22
	v_mul_f32_e32 v191, v24, v24
	v_mul_f32_e32 v192, v18, v18
	v_mul_f32_e32 v193, v20, v20
	v_fmac_f32_e32 v190, v23, v23
	v_fmac_f32_e32 v191, v25, v25
	v_fmac_f32_e32 v192, v19, v19
	v_fmac_f32_e32 v193, v21, v21
	v_cvt_pk_bf16_f32 v202, v22, v23
	v_cvt_pk_bf16_f32 v203, v24, v25
	v_cvt_pk_bf16_f32 v204, v18, v19
	v_cvt_pk_bf16_f32 v205, v20, v21
	v_add_f32_e32 v190, v190, v191
	v_add_f32_e32 v192, v192, v193
	v_add_f32_e32 v190, v190, v192
	v_add_f32_e32 v168, v168, v190
	global_store_dwordx4 v[228:229], v[202:205], off offset:256
	s_cmp_lg_u32 s10, 4
	s_cbranch_scc1 .Lwin_noat_l1_6
	ds_bpermute_b32 v171, v224, v168
	v_ashrrev_i32_e32 v173, 31, v169
	v_mov_b32_e32 v172, v169
	s_waitcnt lgkmcnt(0)
	v_add_f32_e32 v168, v168, v171
	ds_bpermute_b32 v171, v225, v168
	v_lshl_add_u64 v[172:173], v[172:173], 2, s[68:69]
	s_waitcnt lgkmcnt(0)
	v_add_f32_e32 v168, v168, v171
	s_mov_b64 s[84:85], exec
	s_and_b64 exec, exec, s[4:5]
	global_atomic_add_f32 v[172:173], v168, off
	s_mov_b64 exec, s[84:85]
.Lwin_noat_l1_6:
	v_fma_f32 v14, v14, v221, v42
	v_fma_f32 v15, v15, v221, v43
	v_fma_f32 v16, v16, v221, v44
	v_fma_f32 v17, v17, v221, v45
	v_fma_f32 v10, v10, v221, v46
	v_fma_f32 v11, v11, v221, v47
	v_fma_f32 v12, v12, v221, v48
	v_fma_f32 v13, v13, v221, v49
	v_mul_f32_e32 v190, v14, v14
	v_mul_f32_e32 v191, v15, v15
	v_mul_f32_e32 v192, v16, v16
	v_mul_f32_e32 v193, v17, v17
	v_mul_f32_e32 v194, v10, v10
	v_mul_f32_e32 v195, v11, v11
	v_mul_f32_e32 v196, v12, v12
	v_mul_f32_e32 v197, v13, v13
	v_fmaak_f32 v190, v190, v170, 0xc0135761
	v_fmaak_f32 v191, v191, v170, 0xc0135761
	v_fmaak_f32 v192, v192, v170, 0xc0135761
	v_fmaak_f32 v193, v193, v170, 0xc0135761
	v_fmaak_f32 v194, v194, v170, 0xc0135761
	v_fmaak_f32 v195, v195, v170, 0xc0135761
	v_fmaak_f32 v196, v196, v170, 0xc0135761
	v_fmaak_f32 v197, v197, v170, 0xc0135761
	v_add_u32_e32 v169, s23, v182
	v_mad_i64_i32 v[166:167], s[0:1], v169, s22, v[226:227]
	v_mul_f32_e32 v190, v190, v14
	v_mul_f32_e32 v191, v191, v15
	v_mul_f32_e32 v192, v192, v16
	v_mul_f32_e32 v193, v193, v17
	v_mul_f32_e32 v194, v194, v10
	v_mul_f32_e32 v195, v195, v11
	v_mul_f32_e32 v196, v196, v12
	v_mul_f32_e32 v197, v197, v13
	v_exp_f32_e32 v190, v190
	v_exp_f32_e32 v191, v191
	v_exp_f32_e32 v192, v192
	v_exp_f32_e32 v193, v193
	v_exp_f32_e32 v194, v194
	v_exp_f32_e32 v195, v195
	v_exp_f32_e32 v196, v196
	v_exp_f32_e32 v197, v197
	v_add_f32_e32 v190, 1.0, v190
	v_add_f32_e32 v191, 1.0, v191
	v_add_f32_e32 v192, 1.0, v192
	v_add_f32_e32 v193, 1.0, v193
	v_add_f32_e32 v194, 1.0, v194
	v_add_f32_e32 v195, 1.0, v195
	v_add_f32_e32 v196, 1.0, v196
	v_add_f32_e32 v197, 1.0, v197
	v_rcp_f32_e32 v190, v190
	v_rcp_f32_e32 v191, v191
	v_rcp_f32_e32 v192, v192
	v_rcp_f32_e32 v193, v193
	v_rcp_f32_e32 v194, v194
	v_rcp_f32_e32 v195, v195
	v_rcp_f32_e32 v196, v196
	v_rcp_f32_e32 v197, v197
	v_mul_f32_e32 v14, v14, v190
	v_mul_f32_e32 v15, v15, v191
	v_mul_f32_e32 v16, v16, v192
	v_mul_f32_e32 v17, v17, v193
	v_mul_f32_e32 v10, v10, v194
	v_mul_f32_e32 v11, v11, v195
	v_mul_f32_e32 v12, v12, v196
	v_mul_f32_e32 v13, v13, v197
	v_mul_f32_e32 v190, v14, v14
	v_mul_f32_e32 v191, v16, v16
	v_mul_f32_e32 v192, v10, v10
	v_mul_f32_e32 v193, v12, v12
	v_fmac_f32_e32 v190, v15, v15
	v_fmac_f32_e32 v191, v17, v17
	v_fmac_f32_e32 v192, v11, v11
	v_fmac_f32_e32 v193, v13, v13
	v_cvt_pk_bf16_f32 v206, v14, v15
	v_cvt_pk_bf16_f32 v207, v16, v17
	v_cvt_pk_bf16_f32 v208, v10, v11
	v_cvt_pk_bf16_f32 v209, v12, v13
	v_add_f32_e32 v190, v190, v191
	v_add_f32_e32 v192, v192, v193
	v_add_f32_e32 v190, v190, v192
	v_mov_b32_e32 v168, v190
	global_store_dwordx4 v[166:167], v[206:209], off
	v_fma_f32 v6, v6, v221, v38
	v_fma_f32 v7, v7, v221, v39
	v_fma_f32 v8, v8, v221, v40
	v_fma_f32 v9, v9, v221, v41
	v_fma_f32 v2, v2, v221, v34
	v_fma_f32 v3, v3, v221, v35
	v_fma_f32 v4, v4, v221, v36
	v_fma_f32 v5, v5, v221, v37
	v_mul_f32_e32 v190, v6, v6
	v_mul_f32_e32 v191, v7, v7
	v_mul_f32_e32 v192, v8, v8
	v_mul_f32_e32 v193, v9, v9
	v_mul_f32_e32 v194, v2, v2
	v_mul_f32_e32 v195, v3, v3
	v_mul_f32_e32 v196, v4, v4
	v_mul_f32_e32 v197, v5, v5
	v_fmaak_f32 v190, v190, v170, 0xc0135761
	v_fmaak_f32 v191, v191, v170, 0xc0135761
	v_fmaak_f32 v192, v192, v170, 0xc0135761
	v_fmaak_f32 v193, v193, v170, 0xc0135761
	v_fmaak_f32 v194, v194, v170, 0xc0135761
	v_fmaak_f32 v195, v195, v170, 0xc0135761
	v_fmaak_f32 v196, v196, v170, 0xc0135761
	v_fmaak_f32 v197, v197, v170, 0xc0135761
	v_mul_f32_e32 v190, v190, v6
	v_mul_f32_e32 v191, v191, v7
	v_mul_f32_e32 v192, v192, v8
	v_mul_f32_e32 v193, v193, v9
	v_mul_f32_e32 v194, v194, v2
	v_mul_f32_e32 v195, v195, v3
	v_mul_f32_e32 v196, v196, v4
	v_mul_f32_e32 v197, v197, v5
	v_exp_f32_e32 v190, v190
	v_exp_f32_e32 v191, v191
	v_exp_f32_e32 v192, v192
	v_exp_f32_e32 v193, v193
	v_exp_f32_e32 v194, v194
	v_exp_f32_e32 v195, v195
	v_exp_f32_e32 v196, v196
	v_exp_f32_e32 v197, v197
	v_add_f32_e32 v190, 1.0, v190
	v_add_f32_e32 v191, 1.0, v191
	v_add_f32_e32 v192, 1.0, v192
	v_add_f32_e32 v193, 1.0, v193
	v_add_f32_e32 v194, 1.0, v194
	v_add_f32_e32 v195, 1.0, v195
	v_add_f32_e32 v196, 1.0, v196
	v_add_f32_e32 v197, 1.0, v197
	v_rcp_f32_e32 v190, v190
	v_rcp_f32_e32 v191, v191
	v_rcp_f32_e32 v192, v192
	v_rcp_f32_e32 v193, v193
	v_rcp_f32_e32 v194, v194
	v_rcp_f32_e32 v195, v195
	v_rcp_f32_e32 v196, v196
	v_rcp_f32_e32 v197, v197
	v_mul_f32_e32 v6, v6, v190
	v_mul_f32_e32 v7, v7, v191
	v_mul_f32_e32 v8, v8, v192
	v_mul_f32_e32 v9, v9, v193
	v_mul_f32_e32 v2, v2, v194
	v_mul_f32_e32 v3, v3, v195
	v_mul_f32_e32 v4, v4, v196
	v_mul_f32_e32 v5, v5, v197
	v_mul_f32_e32 v190, v6, v6
	v_mul_f32_e32 v191, v8, v8
	v_mul_f32_e32 v192, v2, v2
	v_mul_f32_e32 v193, v4, v4
	v_fmac_f32_e32 v190, v7, v7
	v_fmac_f32_e32 v191, v9, v9
	v_fmac_f32_e32 v192, v3, v3
	v_fmac_f32_e32 v193, v5, v5
	v_cvt_pk_bf16_f32 v210, v6, v7
	v_cvt_pk_bf16_f32 v211, v8, v9
	v_cvt_pk_bf16_f32 v212, v2, v3
	v_cvt_pk_bf16_f32 v213, v4, v5
	v_add_f32_e32 v190, v190, v191
	v_add_f32_e32 v192, v192, v193
	v_add_f32_e32 v190, v190, v192
	v_add_f32_e32 v168, v168, v190
	global_store_dwordx4 v[166:167], v[210:213], off offset:256
	s_cmp_lg_u32 s10, 4
	s_cbranch_scc1 .Lwin_noat_l1_7
	ds_bpermute_b32 v171, v224, v168
	v_ashrrev_i32_e32 v173, 31, v169
	v_mov_b32_e32 v172, v169
	s_waitcnt lgkmcnt(0)
	v_add_f32_e32 v168, v168, v171
	ds_bpermute_b32 v171, v225, v168
	v_lshl_add_u64 v[172:173], v[172:173], 2, s[68:69]
	s_waitcnt lgkmcnt(0)
	v_add_f32_e32 v168, v168, v171
	s_mov_b64 s[84:85], exec
	s_and_b64 exec, exec, s[4:5]
	global_atomic_add_f32 v[172:173], v168, off
	s_mov_b64 exec, s[84:85]
.Lwin_noat_l1_7:
	s_branch .Lwin_end_l1
.Lwin_plain_l1:
	v_fma_f32 v142, v142, v214, v42
	v_fma_f32 v143, v143, v214, v43
	v_fma_f32 v144, v144, v214, v44
	v_fma_f32 v145, v145, v214, v45
	v_fma_f32 v138, v138, v214, v46
	v_fma_f32 v139, v139, v214, v47
	v_fma_f32 v140, v140, v214, v48
	v_fma_f32 v141, v141, v214, v49
	v_add_u32_e32 v169, s23, v1
	v_mad_i64_i32 v[228:229], s[0:1], v169, s22, v[226:227]
	v_cvt_pk_bf16_f32 v198, v142, v143
	v_cvt_pk_bf16_f32 v199, v144, v145
	v_cvt_pk_bf16_f32 v200, v138, v139
	v_cvt_pk_bf16_f32 v201, v140, v141
	global_store_dwordx4 v[228:229], v[198:201], off
	v_fma_f32 v134, v134, v214, v38
	v_fma_f32 v135, v135, v214, v39
	v_fma_f32 v136, v136, v214, v40
	v_fma_f32 v137, v137, v214, v41
	v_fma_f32 v130, v130, v214, v34
	v_fma_f32 v131, v131, v214, v35
	v_fma_f32 v132, v132, v214, v36
	v_fma_f32 v133, v133, v214, v37
	v_cvt_pk_bf16_f32 v202, v134, v135
	v_cvt_pk_bf16_f32 v203, v136, v137
	v_cvt_pk_bf16_f32 v204, v130, v131
	v_cvt_pk_bf16_f32 v205, v132, v133
	global_store_dwordx4 v[228:229], v[202:205], off offset:256
	v_fma_f32 v126, v126, v215, v42
	v_fma_f32 v127, v127, v215, v43
	v_fma_f32 v128, v128, v215, v44
	v_fma_f32 v129, v129, v215, v45
	v_fma_f32 v122, v122, v215, v46
	v_fma_f32 v123, v123, v215, v47
	v_fma_f32 v124, v124, v215, v48
	v_fma_f32 v125, v125, v215, v49
	v_add_u32_e32 v169, s23, v176
	v_mad_i64_i32 v[166:167], s[0:1], v169, s22, v[226:227]
	v_cvt_pk_bf16_f32 v206, v126, v127
	v_cvt_pk_bf16_f32 v207, v128, v129
	v_cvt_pk_bf16_f32 v208, v122, v123
	v_cvt_pk_bf16_f32 v209, v124, v125
	global_store_dwordx4 v[166:167], v[206:209], off
	v_fma_f32 v118, v118, v215, v38
	v_fma_f32 v119, v119, v215, v39
	v_fma_f32 v120, v120, v215, v40
	v_fma_f32 v121, v121, v215, v41
	v_fma_f32 v114, v114, v215, v34
	v_fma_f32 v115, v115, v215, v35
	v_fma_f32 v116, v116, v215, v36
	v_fma_f32 v117, v117, v215, v37
	v_cvt_pk_bf16_f32 v210, v118, v119
	v_cvt_pk_bf16_f32 v211, v120, v121
	v_cvt_pk_bf16_f32 v212, v114, v115
	v_cvt_pk_bf16_f32 v213, v116, v117
	global_store_dwordx4 v[166:167], v[210:213], off offset:256
	v_fma_f32 v110, v110, v216, v42
	v_fma_f32 v111, v111, v216, v43
	v_fma_f32 v112, v112, v216, v44
	v_fma_f32 v113, v113, v216, v45
	v_fma_f32 v106, v106, v216, v46
	v_fma_f32 v107, v107, v216, v47
	v_fma_f32 v108, v108, v216, v48
	v_fma_f32 v109, v109, v216, v49
	v_add_u32_e32 v169, s23, v177
	v_mad_i64_i32 v[228:229], s[0:1], v169, s22, v[226:227]
	v_cvt_pk_bf16_f32 v198, v110, v111
	v_cvt_pk_bf16_f32 v199, v112, v113
	v_cvt_pk_bf16_f32 v200, v106, v107
	v_cvt_pk_bf16_f32 v201, v108, v109
	global_store_dwordx4 v[228:229], v[198:201], off
	v_fma_f32 v102, v102, v216, v38
	v_fma_f32 v103, v103, v216, v39
	v_fma_f32 v104, v104, v216, v40
	v_fma_f32 v105, v105, v216, v41
	v_fma_f32 v98, v98, v216, v34
	v_fma_f32 v99, v99, v216, v35
	v_fma_f32 v100, v100, v216, v36
	v_fma_f32 v101, v101, v216, v37
	v_cvt_pk_bf16_f32 v202, v102, v103
	v_cvt_pk_bf16_f32 v203, v104, v105
	v_cvt_pk_bf16_f32 v204, v98, v99
	v_cvt_pk_bf16_f32 v205, v100, v101
	global_store_dwordx4 v[228:229], v[202:205], off offset:256
	v_fma_f32 v94, v94, v217, v42
	v_fma_f32 v95, v95, v217, v43
	v_fma_f32 v96, v96, v217, v44
	v_fma_f32 v97, v97, v217, v45
	v_fma_f32 v90, v90, v217, v46
	v_fma_f32 v91, v91, v217, v47
	v_fma_f32 v92, v92, v217, v48
	v_fma_f32 v93, v93, v217, v49
	v_add_u32_e32 v169, s23, v178
	v_mad_i64_i32 v[166:167], s[0:1], v169, s22, v[226:227]
	v_cvt_pk_bf16_f32 v206, v94, v95
	v_cvt_pk_bf16_f32 v207, v96, v97
	v_cvt_pk_bf16_f32 v208, v90, v91
	v_cvt_pk_bf16_f32 v209, v92, v93
	global_store_dwordx4 v[166:167], v[206:209], off
	v_fma_f32 v86, v86, v217, v38
	v_fma_f32 v87, v87, v217, v39
	v_fma_f32 v88, v88, v217, v40
	v_fma_f32 v89, v89, v217, v41
	v_fma_f32 v82, v82, v217, v34
	v_fma_f32 v83, v83, v217, v35
	v_fma_f32 v84, v84, v217, v36
	v_fma_f32 v85, v85, v217, v37
	v_cvt_pk_bf16_f32 v210, v86, v87
	v_cvt_pk_bf16_f32 v211, v88, v89
	v_cvt_pk_bf16_f32 v212, v82, v83
	v_cvt_pk_bf16_f32 v213, v84, v85
	global_store_dwordx4 v[166:167], v[210:213], off offset:256
	v_fma_f32 v78, v78, v218, v42
	v_fma_f32 v79, v79, v218, v43
	v_fma_f32 v80, v80, v218, v44
	v_fma_f32 v81, v81, v218, v45
	v_fma_f32 v74, v74, v218, v46
	v_fma_f32 v75, v75, v218, v47
	v_fma_f32 v76, v76, v218, v48
	v_fma_f32 v77, v77, v218, v49
	v_add_u32_e32 v169, s23, v179
	v_mad_i64_i32 v[228:229], s[0:1], v169, s22, v[226:227]
	v_cvt_pk_bf16_f32 v198, v78, v79
	v_cvt_pk_bf16_f32 v199, v80, v81
	v_cvt_pk_bf16_f32 v200, v74, v75
	v_cvt_pk_bf16_f32 v201, v76, v77
	global_store_dwordx4 v[228:229], v[198:201], off
	v_fma_f32 v70, v70, v218, v38
	v_fma_f32 v71, v71, v218, v39
	v_fma_f32 v72, v72, v218, v40
	v_fma_f32 v73, v73, v218, v41
	v_fma_f32 v66, v66, v218, v34
	v_fma_f32 v67, v67, v218, v35
	v_fma_f32 v68, v68, v218, v36
	v_fma_f32 v69, v69, v218, v37
	v_cvt_pk_bf16_f32 v202, v70, v71
	v_cvt_pk_bf16_f32 v203, v72, v73
	v_cvt_pk_bf16_f32 v204, v66, v67
	v_cvt_pk_bf16_f32 v205, v68, v69
	global_store_dwordx4 v[228:229], v[202:205], off offset:256
	v_fma_f32 v62, v62, v219, v42
	v_fma_f32 v63, v63, v219, v43
	v_fma_f32 v64, v64, v219, v44
	v_fma_f32 v65, v65, v219, v45
	v_fma_f32 v58, v58, v219, v46
	v_fma_f32 v59, v59, v219, v47
	v_fma_f32 v60, v60, v219, v48
	v_fma_f32 v61, v61, v219, v49
	v_add_u32_e32 v169, s23, v180
	v_mad_i64_i32 v[166:167], s[0:1], v169, s22, v[226:227]
	v_cvt_pk_bf16_f32 v206, v62, v63
	v_cvt_pk_bf16_f32 v207, v64, v65
	v_cvt_pk_bf16_f32 v208, v58, v59
	v_cvt_pk_bf16_f32 v209, v60, v61
	global_store_dwordx4 v[166:167], v[206:209], off
	v_fma_f32 v54, v54, v219, v38
	v_fma_f32 v55, v55, v219, v39
	v_fma_f32 v56, v56, v219, v40
	v_fma_f32 v57, v57, v219, v41
	v_fma_f32 v50, v50, v219, v34
	v_fma_f32 v51, v51, v219, v35
	v_fma_f32 v52, v52, v219, v36
	v_fma_f32 v53, v53, v219, v37
	v_cvt_pk_bf16_f32 v210, v54, v55
	v_cvt_pk_bf16_f32 v211, v56, v57
	v_cvt_pk_bf16_f32 v212, v50, v51
	v_cvt_pk_bf16_f32 v213, v52, v53
	global_store_dwordx4 v[166:167], v[210:213], off offset:256
	v_fma_f32 v30, v30, v220, v42
	v_fma_f32 v31, v31, v220, v43
	v_fma_f32 v32, v32, v220, v44
	v_fma_f32 v33, v33, v220, v45
	v_fma_f32 v26, v26, v220, v46
	v_fma_f32 v27, v27, v220, v47
	v_fma_f32 v28, v28, v220, v48
	v_fma_f32 v29, v29, v220, v49
	v_add_u32_e32 v169, s23, v181
	v_mad_i64_i32 v[228:229], s[0:1], v169, s22, v[226:227]
	v_cvt_pk_bf16_f32 v198, v30, v31
	v_cvt_pk_bf16_f32 v199, v32, v33
	v_cvt_pk_bf16_f32 v200, v26, v27
	v_cvt_pk_bf16_f32 v201, v28, v29
	global_store_dwordx4 v[228:229], v[198:201], off
	v_fma_f32 v22, v22, v220, v38
	v_fma_f32 v23, v23, v220, v39
	v_fma_f32 v24, v24, v220, v40
	v_fma_f32 v25, v25, v220, v41
	v_fma_f32 v18, v18, v220, v34
	v_fma_f32 v19, v19, v220, v35
	v_fma_f32 v20, v20, v220, v36
	v_fma_f32 v21, v21, v220, v37
	v_cvt_pk_bf16_f32 v202, v22, v23
	v_cvt_pk_bf16_f32 v203, v24, v25
	v_cvt_pk_bf16_f32 v204, v18, v19
	v_cvt_pk_bf16_f32 v205, v20, v21
	global_store_dwordx4 v[228:229], v[202:205], off offset:256
	v_fma_f32 v14, v14, v221, v42
	v_fma_f32 v15, v15, v221, v43
	v_fma_f32 v16, v16, v221, v44
	v_fma_f32 v17, v17, v221, v45
	v_fma_f32 v10, v10, v221, v46
	v_fma_f32 v11, v11, v221, v47
	v_fma_f32 v12, v12, v221, v48
	v_fma_f32 v13, v13, v221, v49
	v_add_u32_e32 v169, s23, v182
	v_mad_i64_i32 v[166:167], s[0:1], v169, s22, v[226:227]
	v_cvt_pk_bf16_f32 v206, v14, v15
	v_cvt_pk_bf16_f32 v207, v16, v17
	v_cvt_pk_bf16_f32 v208, v10, v11
	v_cvt_pk_bf16_f32 v209, v12, v13
	global_store_dwordx4 v[166:167], v[206:209], off
	v_fma_f32 v6, v6, v221, v38
	v_fma_f32 v7, v7, v221, v39
	v_fma_f32 v8, v8, v221, v40
	v_fma_f32 v9, v9, v221, v41
	v_fma_f32 v2, v2, v221, v34
	v_fma_f32 v3, v3, v221, v35
	v_fma_f32 v4, v4, v221, v36
	v_fma_f32 v5, v5, v221, v37
	v_cvt_pk_bf16_f32 v210, v6, v7
	v_cvt_pk_bf16_f32 v211, v8, v9
	v_cvt_pk_bf16_f32 v212, v2, v3
	v_cvt_pk_bf16_f32 v213, v4, v5
	global_store_dwordx4 v[166:167], v[210:213], off offset:256
.Lwin_end_l1:
.LBB0_1090:
	s_andn2_b64 vcc, exec, s[6:7]
	s_mov_b64 s[0:1], -1
	s_cbranch_vccnz .LBB0_983
	s_andn2_b64 vcc, exec, s[28:29]
	s_cbranch_vccnz .LBB0_982
	s_barrier
	s_branch .LBB0_982
